# stagger: 32 distinct delays per XCD, step 256 cycles
# speedup vs baseline: 1.1124x; 1.0012x over previous
.LBB0_96:
	s_lshl_b32 s2, 1, s55
	s_and_b32 s2, s2, 0x4444
	s_cbranch_scc0 .Lstg_skip
	s_lshr_b32 s2, s54, 3
	s_and_b32 s2, s2, 31
.Lstg_loop:
	s_cmp_eq_u32 s2, 0
	s_cbranch_scc1 .Lstg_skip
	s_sleep 4
	s_sub_u32 s2, s2, 1
	s_branch .Lstg_loop
